# sample attention image writes of the conversion pass: addresses from one per-unit lane constant and three XOR/add variants instead of ~45 VALU of swizzle arithmetic per tile
# baseline (speedup 1.0000x reference)
.LBB0_800:
	s_or_b64 exec, exec, s[0:1]
	v_and_b32_e32 v215, 15, v250
	v_lshl_or_b32 v2, s19, 7, v215
	v_ashrrev_i32_e32 v3, 31, v2
	v_readlane_b32 s40, v253, 24
	v_lshlrev_b64 v[2:3], 9, v[2:3]
	v_readlane_b32 s48, v253, 32
	v_readlane_b32 s49, v253, 33
	s_movk_i32 s0, 0x2000
	s_and_b32 s8, s14, 0x80000001
	v_lshl_add_u64 v[4:5], s[48:49], 0, v[2:3]
	v_and_b32_e32 v2, 48, v214
	v_mov_b32_e32 v3, v191
	v_lshl_add_u64 v[4:5], v[4:5], 0, v[2:3]
	v_add_co_u32_e32 v10, vcc, s0, v4
	s_movk_i32 s0, 0x4000
	s_nop 0
	v_addc_co_u32_e32 v11, vcc, 0, v5, vcc
	global_load_dwordx4 v[50:53], v[4:5], off
	global_load_dwordx4 v[54:57], v[4:5], off offset:64
	global_load_dwordx4 v[58:61], v[4:5], off offset:128
	global_load_dwordx4 v[62:65], v[4:5], off offset:192
	global_load_dwordx4 v[66:69], v[4:5], off offset:256
	global_load_dwordx4 v[70:73], v[4:5], off offset:320
	global_load_dwordx4 v[74:77], v[4:5], off offset:384
	global_load_dwordx4 v[78:81], v[4:5], off offset:448
	global_load_dwordx4 v[82:85], v[10:11], off
	global_load_dwordx4 v[86:89], v[10:11], off offset:64
	global_load_dwordx4 v[90:93], v[10:11], off offset:128
	global_load_dwordx4 v[94:97], v[10:11], off offset:192
	global_load_dwordx4 v[98:101], v[10:11], off offset:256
	global_load_dwordx4 v[102:105], v[10:11], off offset:320
	global_load_dwordx4 v[106:109], v[10:11], off offset:384
	global_load_dwordx4 v[110:113], v[10:11], off offset:448
	v_add_co_u32_e32 v10, vcc, s0, v4
	s_movk_i32 s0, 0x6000
	s_nop 0
	v_addc_co_u32_e32 v11, vcc, 0, v5, vcc
	v_add_co_u32_e32 v4, vcc, s0, v4
	global_load_dwordx4 v[114:117], v[10:11], off
	global_load_dwordx4 v[118:121], v[10:11], off offset:64
	global_load_dwordx4 v[122:125], v[10:11], off offset:128
	global_load_dwordx4 v[126:129], v[10:11], off offset:192
	global_load_dwordx4 v[130:133], v[10:11], off offset:256
	global_load_dwordx4 v[134:137], v[10:11], off offset:320
	global_load_dwordx4 v[138:141], v[10:11], off offset:384
	global_load_dwordx4 v[142:145], v[10:11], off offset:448
	v_addc_co_u32_e32 v5, vcc, 0, v5, vcc
	global_load_dwordx4 v[146:149], v[4:5], off
	global_load_dwordx4 v[150:153], v[4:5], off offset:64
	global_load_dwordx4 v[154:157], v[4:5], off offset:128
	global_load_dwordx4 v[158:161], v[4:5], off offset:192
	global_load_dwordx4 v[162:165], v[4:5], off offset:256
	global_load_dwordx4 v[166:169], v[4:5], off offset:320
	global_load_dwordx4 v[170:173], v[4:5], off offset:384
	global_load_dwordx4 v[174:177], v[4:5], off offset:448
	v_add_u32_e32 v4, s15, v215
	s_movk_i32 s0, 0x68
	v_mul_lo_u32 v4, v4, s0
	v_cmp_gt_u32_e64 s[0:1], 8, v215
	s_cmp_eq_u32 s8, 1
	s_cselect_b32 s37, 0x41, 64
	v_cndmask_b32_e64 v34, v210, v4, s[0:1]
	v_mov_b32_e32 v4, v0
	s_add_i32 s38, 0, 0x1f400
	s_lshl_b32 s11, s18, 6
	s_and_b32 s11, s11, 0xffffc000
	s_add_i32 s39, s11, 0
	s_lshl_b32 s11, s19, 2
	v_readlane_b32 s44, v253, 28
	v_readlane_b32 s45, v253, 29
	v_readlane_b32 s46, v253, 30
	v_readlane_b32 s47, v253, 31
	v_readlane_b32 s50, v253, 34
	v_readlane_b32 s51, v253, 35
	v_readlane_b32 s52, v253, 36
	v_readlane_b32 s53, v253, 37
	v_readlane_b32 s54, v253, 38
	v_readlane_b32 s55, v253, 39
	v_lshrrev_b32_e32 v3, 4, v214
	s_and_b32 s40, s11, 12
	v_lshl_add_u32 v221, v7, 2, 0
	s_movk_i32 s11, 0x8c
	v_lshlrev_b32_e32 v216, 3, v3
	v_lshlrev_b32_e32 v218, 2, v3
	v_mad_u32_u24 v3, v7, s11, v221
	s_movk_i32 s11, 0x800
	v_readlane_b32 s44, v254, 28
	v_readlane_b32 s42, v253, 26
	v_readlane_b32 s43, v253, 27
	v_cmp_gt_i32_e64 s[12:13], s11, v250
	s_movk_i32 s11, 0xff72
	v_readlane_b32 s46, v254, 30
	v_readlane_b32 s47, v254, 31
	v_mad_i32_i24 v194, v7, s11, v3
	v_lshl_add_u64 v[196:197], s[84:85], 0, v[190:191]
	v_lshlrev_b32_e32 v190, 4, v7
	v_readlane_b32 s45, v254, 29
	v_readlane_b32 s48, v254, 32
	v_readlane_b32 s49, v254, 33
	v_readlane_b32 s50, v254, 34
	v_readlane_b32 s51, v254, 35
	v_readlane_b32 s52, v254, 36
	v_readlane_b32 s53, v254, 37
	s_waitcnt vmcnt(0)
	s_waitcnt vmcnt(0)
	v_readlane_b32 s54, v254, 38
	v_lshrrev_b32_e32 v5, 3, v4
	v_bfe_u32 v8, v4, 5, 1
	v_and_or_b32 v5, v5, s28, v8
	v_lshlrev_b32_e32 v8, 5, v4
	v_and_b32_e32 v8, 0x3e0, v8
	v_lshlrev_b32_e32 v5, 10, v5
	v_add3_u32 v5, 0, v8, v5
	ds_read_b128 v[10:13], v5 offset:62464
	ds_read_b128 v[14:17], v5 offset:62480
	v_add_u32_e32 v8, 0xf400, v5
	ds_read_b128 v[18:21], v5 offset:64512
	ds_read_b128 v[22:25], v8 offset:4096
	ds_read_b128 v[26:29], v8 offset:4112
	s_waitcnt lgkmcnt(0)
	v_cvt_pk_bf16_f32 v10, v10, v11
	v_cvt_pk_bf16_f32 v11, v12, v13
	v_cvt_pk_bf16_f32 v12, v14, v15
	v_cvt_pk_bf16_f32 v13, v16, v17
	ds_read_b128 v[14:17], v5 offset:64528
	v_lshlrev_b32_e32 v4, 4, v4
	v_and_b32_e32 v5, 0xffffff80, v4
	v_and_b32_e32 v4, 0x70, v4
	v_cvt_pk_bf16_f32 v18, v18, v19
	v_cvt_pk_bf16_f32 v19, v20, v21
	s_waitcnt lgkmcnt(0)
	v_cvt_pk_bf16_f32 v20, v14, v15
	v_cvt_pk_bf16_f32 v21, v16, v17
	v_cvt_pk_bf16_f32 v14, v22, v23
	v_cvt_pk_bf16_f32 v15, v24, v25
	v_cvt_pk_bf16_f32 v16, v26, v27
	v_cvt_pk_bf16_f32 v17, v28, v29
	ds_read_b128 v[22:25], v8 offset:6144
	ds_read_b128 v[26:29], v8 offset:6160
	v_add3_u32 v4, s38, v5, v4
	ds_read_b128 v[30:33], v4
	v_mov_b32_e32 v8, v0
	s_waitcnt lgkmcnt(2)
	v_cvt_pk_bf16_f32 v22, v22, v23
	v_cvt_pk_bf16_f32 v23, v24, v25
	s_waitcnt lgkmcnt(1)
	v_cvt_pk_bf16_f32 v24, v26, v27
	v_cvt_pk_bf16_f32 v25, v28, v29
	v_ashrrev_i32_e32 v26, 3, v8
	s_waitcnt lgkmcnt(0)
	v_cvt_pk_bf16_f32 v5, v32, v33
	v_bfe_u32 v28, v8, 5, 1
	v_lshrrev_b32_e32 v33, 2, v26
	v_cvt_pk_bf16_f32 v4, v30, v31
	v_and_b32_e32 v27, -8, v26
	v_lshlrev_b32_e32 v29, 10, v8
	v_and_b32_e32 v30, 15, v8
	v_and_b32_e32 v33, 2, v33
	v_lshlrev_b32_e32 v35, 2, v28
	v_and_b32_e32 v29, 0x4000, v29
	v_or_b32_e32 v31, v27, v28
	v_bitop3_b32 v36, v35, v30, v33 bitop3:0x36
	v_add_u32_e32 v29, 0, v29
	v_lshlrev_b32_e32 v32, 8, v31
	v_lshlrev_b32_e32 v36, 4, v36
	v_add3_u32 v32, v29, v36, v32
	ds_write_b128 v32, v[10:13]
	v_or_b32_e32 v10, 2, v31
	v_lshlrev_b32_e32 v11, 8, v10
	v_lshlrev_b32_e32 v10, 2, v10
	v_and_b32_e32 v10, 12, v10
	v_bitop3_b32 v10, v10, v30, v33 bitop3:0x36
	v_lshlrev_b32_e32 v10, 4, v10
	v_add3_u32 v10, v29, v10, v11
	ds_write_b128 v10, v[18:21]
	v_or_b32_e32 v10, 4, v27
	v_or_b32_e32 v11, v10, v28
	v_bfe_u32 v10, v10, 2, 2
	v_bitop3_b32 v10, v35, v30, v10 bitop3:0x36
	v_lshlrev_b32_e32 v11, 8, v11
	v_lshlrev_b32_e32 v10, 4, v10
	v_add3_u32 v10, v29, v10, v11
	ds_write_b128 v10, v[14:17]
	v_or_b32_e32 v10, 6, v27
	v_or_b32_e32 v11, v10, v28
	v_lshlrev_b32_e32 v12, 8, v11
	v_lshlrev_b32_e32 v11, 2, v11
	v_and_b32_e32 v11, 12, v11
	v_bfe_u32 v10, v10, 2, 2
	v_bitop3_b32 v10, v11, v30, v10 bitop3:0x36
	v_lshlrev_b32_e32 v10, 4, v10
	v_lshlrev_b32_e32 v8, 2, v8
	v_add3_u32 v10, v29, v10, v12
	v_and_b32_e32 v8, 28, v8
	ds_write_b128 v10, v[22:25]
	v_mad_u64_u32 v[10:11], s[8:9], v26, 40, v[8:9]
	v_lshl_add_u32 v8, v10, 1, 0
	ds_write_b64 v8, v[4:5] offset:32768
	v_lshlrev_b32_e32 v4, 1, v34
	v_add3_u32 v219, 0, v4, v216
	v_lshrrev_b32_e32 v4, 1, v250
	v_readlane_b32 s55, v254, 39
	s_mov_b64 s[42:43], s[46:47]
	s_lshl_b32 s11, s19, 5
	v_and_b32_e32 v4, 16, v4
	v_readlane_b32 s56, v254, 40
	v_readlane_b32 s57, v254, 41
	v_readlane_b32 s58, v254, 42
	v_readlane_b32 s59, v254, 43
	s_mov_b64 s[44:45], s[48:49]
	v_lshl_add_u64 v[198:199], s[42:43], 0, v[190:191]
	v_lshlrev_b32_e32 v190, 1, v7
	s_add_i32 s11, s11, 0xecd0
	s_waitcnt lgkmcnt(0)
	s_barrier
	v_add_u32_e32 v222, v3, v4
	v_lshlrev_b32_e32 v4, 10, v7
	v_lshl_add_u64 v[200:201], s[44:45], 0, v[190:191]
	v_lshl_add_u32 v190, v215, 2, s11
	s_mul_i32 s11, s19, 0x480
	v_and_b32_e32 v4, 0x4000, v4
	v_mov_b32_e32 v7, v191
	s_add_i32 s11, s11, 0x9400
	v_mul_u32_u24_e32 v3, 0x90, v215
	v_mad_u32_u24 v2, v215, s29, v2
	v_mov_b32_e32 v217, 0
	s_mov_b32 s10, 0
	v_mov_b32_e32 v193, s17
	v_or_b32_e32 v192, s15, v9
	v_min_u32_e32 v220, 7, v215
	v_cmp_gt_u32_e64 s[8:9], 16, v214
	v_add_u32_e32 v223, 0, v4
	v_lshl_add_u64 v[212:213], s[82:83], 0, v[6:7]
	v_add3_u32 v224, s11, v3, v216
	v_or_b32_e32 v225, 0x8000, v2
	v_mov_b32_e32 v42, 0xff800000
	v_mov_b32_e32 v2, 0
	v_mov_b32_e32 v3, v217
	v_mov_b32_e32 v4, v217
	v_mov_b32_e32 v5, v217
	v_mov_b32_e32 v6, v217
	v_mov_b32_e32 v7, v217
	v_mov_b32_e32 v8, v217
	v_mov_b32_e32 v9, v217
	v_mov_b32_e32 v10, v217
	v_mov_b32_e32 v11, v217
	v_mov_b32_e32 v12, v217
	v_mov_b32_e32 v13, v217
	v_mov_b32_e32 v14, v217
	v_mov_b32_e32 v15, v217
	v_mov_b32_e32 v16, v217
	v_mov_b32_e32 v17, v217
	v_mov_b32_e32 v18, 0
	v_mov_b32_e32 v19, v217
	v_mov_b32_e32 v20, v217
	v_mov_b32_e32 v21, v217
	v_mov_b32_e32 v22, v217
	v_mov_b32_e32 v23, v217
	v_mov_b32_e32 v24, v217
	v_mov_b32_e32 v25, v217
	v_mov_b32_e32 v26, v217
	v_mov_b32_e32 v27, v217
	v_mov_b32_e32 v28, v217
	v_mov_b32_e32 v29, v217
	v_mov_b32_e32 v30, v217
	v_mov_b32_e32 v31, v217
	v_mov_b32_e32 v32, v217
	v_mov_b32_e32 v33, v217
	v_readlane_b32 s41, v253, 25
	s_mov_b64 s[46:47], s[50:51]
	s_mov_b64 s[48:49], s[52:53]
	s_mov_b64 s[50:51], s[54:55]
	s_mov_b64 s[52:53], s[56:57]
	s_mov_b64 s[54:55], s[58:59]
	v_lshrrev_b32_e32 v45, 4, v214
	v_lshlrev_b32_e32 v34, 2, v214
	v_and_b32_e32 v34, 12, v34
	v_bfe_u32 v35, v214, 2, 2
	v_add_u32_e32 v38, 8, v45
	v_add_u32_e32 v37, 4, v45
	v_bitop3_b32 v47, v34, v38, v35 bitop3:0x36
	v_add_u32_e32 v38, 12, v45
	v_bitop3_b32 v36, v34, v45, v35 bitop3:0x36
	v_bitop3_b32 v37, v34, v37, v35 bitop3:0x36
	v_bitop3_b32 v46, v34, v38, v35 bitop3:0x36
	v_lshlrev_b32_e32 v34, 8, v214
	v_and_b32_e32 v34, 0xf00, v34
	v_lshrrev_b32_e32 v44, 2, v214
	v_lshl_add_u32 v46, v46, 4, v34
	v_lshl_add_u32 v47, v47, 4, v34
	v_lshl_add_u32 v48, v37, 4, v34
	v_lshl_add_u32 v49, v36, 4, v34
	v_lshrrev_b32_e32 v34, 3, v214
	v_and_b32_e32 v38, 12, v214
	v_and_or_b32 v34, v34, 2, s40
	v_bfe_u32 v35, v214, 1, 1
	v_and_or_b32 v39, v45, 2, v38
	v_or_b32_e32 v36, v34, v35
	v_lshlrev_b32_e32 v37, 8, v44
	v_bitop3_b32 v34, v34, v39, v35 bitop3:0x36
	v_lshlrev_b32_e32 v35, 3, v214
	v_and_b32_e32 v37, 0xfffffb00, v37
	v_and_b32_e32 v35, 8, v35
	v_lshl_add_u32 v34, v34, 4, s39
	v_add3_u32 v34, v34, v37, v35
	v_or_b32_e32 v37, 4, v44
	v_lshlrev_b32_e32 v39, 8, v37
	v_bfe_u32 v37, v37, 2, 2
	v_bitop3_b32 v36, v37, v36, v38 bitop3:0x36
	v_lshl_add_u32 v36, v36, 4, s39
	v_add3_u32 v35, v36, v39, v35
	v_mov_b32_e32 v43, v34
	v_mov_b32_e32 v44, v35
	v_lshrrev_b32_e32 v34, 6, v0
	v_bfe_u32 v35, v0, 5, 1
	v_lshl_add_u32 v36, v34, 3, v35
	v_lshlrev_b32_e32 v37, 1, v34
	v_and_b32_e32 v37, 3, v37
	v_lshl_or_b32 v37, v35, 2, v37
	v_and_b32_e32 v38, 15, v0
	v_xor_b32_e32 v37, v38, v37
	v_lshlrev_b32_e32 v37, 4, v37
	v_lshl_or_b32 v37, v36, 8, v37
	v_bfe_u32 v38, v0, 4, 1
	v_lshl_or_b32 v45, v38, 14, v37

.Lsa_pdone:
	s_or_b64 exec, exec, s[24:25]
	v_add_u32_e32 v40, 0xec00, v221
	s_waitcnt lgkmcnt(0)
	s_barrier
	ds_read2_b32 v[202:203], v40 offset0:52 offset1:84
	ds_read_b64_tr_b16 v[226:227], v43
	ds_read_b64_tr_b16 v[228:229], v44
	ds_read_b64_tr_b16 v[186:187], v43 offset:4096
	ds_read_b64_tr_b16 v[188:189], v44 offset:4096
	ds_read_b64_tr_b16 v[182:183], v43 offset:8192
	ds_read_b64_tr_b16 v[184:185], v44 offset:8192
	ds_read_b64_tr_b16 v[178:179], v43 offset:12288
	ds_read_b64_tr_b16 v[180:181], v44 offset:12288
	s_waitcnt lgkmcnt(8)
	v_pk_mul_f32 v[2:3], v[202:203], v[2:3] op_sel_hi:[0,1]
	v_pk_mul_f32 v[4:5], v[202:203], v[4:5] op_sel_hi:[0,1]
	v_pk_mul_f32 v[6:7], v[202:203], v[6:7] op_sel_hi:[0,1]
	v_pk_mul_f32 v[8:9], v[202:203], v[8:9] op_sel_hi:[0,1]
	v_pk_mul_f32 v[10:11], v[202:203], v[10:11] op_sel_hi:[0,1]
	v_pk_mul_f32 v[12:13], v[202:203], v[12:13] op_sel_hi:[0,1]
	v_pk_mul_f32 v[14:15], v[202:203], v[14:15] op_sel_hi:[0,1]
	v_pk_mul_f32 v[16:17], v[202:203], v[16:17] op_sel_hi:[0,1]
	v_pk_mul_f32 v[18:19], v[202:203], v[18:19] op_sel:[1,0]
	v_pk_mul_f32 v[20:21], v[202:203], v[20:21] op_sel:[1,0]
	v_pk_mul_f32 v[22:23], v[202:203], v[22:23] op_sel:[1,0]
	v_pk_mul_f32 v[24:25], v[202:203], v[24:25] op_sel:[1,0]
	v_pk_mul_f32 v[26:27], v[202:203], v[26:27] op_sel:[1,0]
	v_pk_mul_f32 v[28:29], v[202:203], v[28:29] op_sel:[1,0]
	v_pk_mul_f32 v[30:31], v[202:203], v[30:31] op_sel:[1,0]
	v_pk_mul_f32 v[32:33], v[202:203], v[32:33] op_sel:[1,0]
	s_waitcnt lgkmcnt(4)
	ds_read_b128 v[230:233], v222 offset:37888
	ds_read_b128 v[234:237], v222 offset:42496
	ds_read_b128 v[238:241], v222 offset:37920
	ds_read_b128 v[242:245], v222 offset:42528
	ds_read_b128 v[246:249], v222 offset:37952
	ds_read_b128 v[206:209], v222 offset:42560
	ds_read_b128 v[34:37], v222 offset:37984
	ds_read_b128 v[38:41], v222 offset:42592
	v_lshrrev_b32_e32 v202, 3, v0
	v_bfe_u32 v203, v0, 5, 1
	v_and_or_b32 v202, v202, s28, v203
	v_lshlrev_b32_e32 v203, 5, v0
	v_and_b32_e32 v203, 0x3e0, v203
	v_lshlrev_b32_e32 v202, 10, v202
	v_add3_u32 v42, 0, v203, v202
	v_lshlrev_b32_e32 v202, 4, v0
	v_and_b32_e32 v203, 0xffffff80, v202
	v_and_b32_e32 v202, 0x70, v202
	v_add3_u32 v205, s38, v203, v202
	v_add_u32_e32 v203, 0xf400, v42
	s_and_b64 vcc, exec, s[18:19]
	s_waitcnt lgkmcnt(0)
	s_barrier
	v_mfma_f32_32x32x16_bf16 v[2:17], v[226:229], v[230:233], v[2:17]
	v_mfma_f32_32x32x16_bf16 v[18:33], v[226:229], v[234:237], v[18:33]
	s_cbranch_vccnz .Lsa_cv0
	s_waitcnt vmcnt(0)
	ds_read_b128 v[226:229], v42 offset:64512
	ds_read_b128 v[230:233], v42 offset:64528
	ds_read_b128 v[234:237], v203 offset:4096
.Lsa_cv0:
	v_mfma_f32_32x32x16_bf16 v[2:17], v[186:189], v[238:241], v[2:17]
	v_mfma_f32_32x32x16_bf16 v[18:33], v[186:189], v[242:245], v[18:33]
	s_cbranch_vccnz .Lsa_cv1
	ds_read_b128 v[238:241], v203 offset:4112
	ds_read_b128 v[242:245], v203 offset:6144
.Lsa_cv1:
	v_mfma_f32_32x32x16_bf16 v[2:17], v[182:185], v[246:249], v[2:17]
	v_mfma_f32_32x32x16_bf16 v[18:33], v[182:185], v[206:209], v[18:33]
	s_cbranch_vccnz .Lsa_cv2
	ds_read_b128 v[246:249], v203 offset:6160

.LBB0_825:
	s_andn2_b64 vcc, exec, s[10:11]
	s_cbranch_vccnz .LBB0_827
	s_waitcnt lgkmcnt(0)
	v_cvt_pk_bf16_f32 v34, v34, v35
	v_cvt_pk_bf16_f32 v35, v36, v37
	v_cvt_pk_bf16_f32 v36, v38, v39
	v_cvt_pk_bf16_f32 v37, v40, v41
	v_cvt_pk_bf16_f32 v226, v226, v227
	v_cvt_pk_bf16_f32 v227, v228, v229
	v_cvt_pk_bf16_f32 v228, v230, v231
	v_cvt_pk_bf16_f32 v229, v232, v233
	v_cvt_pk_bf16_f32 v234, v234, v235
	v_cvt_pk_bf16_f32 v235, v236, v237
	v_cvt_pk_bf16_f32 v236, v238, v239
	v_cvt_pk_bf16_f32 v237, v240, v241
	v_cvt_pk_bf16_f32 v242, v242, v243
	v_cvt_pk_bf16_f32 v243, v244, v245
	v_cvt_pk_bf16_f32 v244, v246, v247
	v_cvt_pk_bf16_f32 v245, v248, v249
	s_waitcnt lgkmcnt(0)
	v_cvt_pk_bf16_f32 v178, v178, v179
	v_cvt_pk_bf16_f32 v179, v180, v181
	ds_write_b128 v45, v[34:37]
	v_xor_b32_e32 v202, 0x80, v45
	v_add_u32_e32 v202, 0x200, v202
	ds_write_b128 v202, v[226:229]
	v_xor_b32_e32 v42, 16, v45
	v_add_u32_e32 v42, 0x400, v42
	ds_write_b128 v42, v[234:237]
	v_xor_b32_e32 v203, 0x90, v45
	v_add_u32_e32 v203, 0x600, v203
	ds_write_b128 v203, v[242:245]
	v_lshrrev_b32_e32 v202, 3, v0
	v_and_b32_e32 v205, 7, v0
	v_mul_u32_u24_e32 v202, 0x50, v202
	v_lshl_add_u32 v202, v205, 3, v202
	ds_write_b64 v202, v[178:179] offset:32768
